# GEMM K-loop: peeled first iteration for units after the first (SrcC=0 first MFMAs, no zero fill; first two counted waits leave epilogue stores outstanding)
# speedup vs baseline: 1.0229x; 1.0115x over previous
.LBB0_323:
	s_add_i32 m0, s9, 0x18000
	v_lshl_add_u64 v[8:9], v[8:9], 0, s[12:13]
	s_waitcnt vmcnt(2)
	s_barrier
	global_load_lds_dwordx4 v[8:9], off
	v_lshl_add_u64 v[4:5], v[4:5], 0, s[12:13]
	s_add_i32 m0, s9, 0x1a000
	s_add_i32 s77, s9, 0x8000
	global_load_lds_dwordx4 v[4:5], off
	v_lshl_add_u64 v[4:5], v[6:7], 0, s[12:13]
	s_mov_b32 m0, s77
	s_add_i32 s86, s9, 0xa000
	global_load_lds_dwordx4 v[4:5], off
	v_lshl_add_u64 v[4:5], v[10:11], 0, s[12:13]
	s_mov_b32 m0, s86
	v_lshl_add_u64 v[2:3], v[2:3], 0, s[12:13]
	global_load_lds_dwordx4 v[4:5], off
	s_add_i32 m0, s9, 0x1c000
	v_lshl_add_u64 v[0:1], v[0:1], 0, s[12:13]
	global_load_lds_dwordx4 v[2:3], off
	s_add_i32 m0, s9, 0x1e000
	s_and_b32 s48, s0, 3
	global_load_lds_dwordx4 v[0:1], off
	v_bfe_u32 v0, v12, 4, 2
	v_and_b32_e32 v1, 15, v12
	v_lshlrev_b32_e32 v3, 4, v0
	v_lshl_or_b32 v146, s1, 6, v1
	v_lshl_or_b32 v1, v1, 6, v3
	v_lshlrev_b32_e32 v3, 2, v12
	s_lshr_b32 s64, s52, 6
	s_lshl_b32 s0, s1, 13
	v_and_b32_e32 v3, 32, v3
	v_bitop3_b32 v4, v1, s0, v3 bitop3:0xde
	s_lshl_b32 s0, s48, 12
	s_add_i32 s87, s64, -2
	s_cmpk_lt_u32 s38, 0x100
	v_bitop3_b32 v147, v1, s0, v3 bitop3:0xde
	s_cselect_b64 s[0:1], -1, 0
	s_lshl_b32 s65, s50, 2
	v_cvt_f32_u32_e32 v1, s65
	v_lshlrev_b32_e32 v2, 3, v0
	v_writelane_b32 v233, s0, 50
	v_cmp_eq_u32_e64 s[38:39], 0, v0
	v_rcp_iflag_f32_e32 v0, v1
	v_writelane_b32 v233, s1, 51
	s_mov_b32 s0, s54
	s_mov_b32 s1, s47
	s_mov_b64 s[62:63], s[0:1]
	v_readlane_b32 s0, v233, 58
	s_lshr_b32 s61, s54, 3
	v_readlane_b32 s1, v233, 59
	s_and_b64 s[0:1], s[0:1], exec
	v_mul_f32_e32 v0, 0x4f7ffffe, v0
	v_readlane_b32 s0, v232, 2
	v_readlane_b32 s40, v233, 56
	v_cvt_u32_f32_e32 v0, v0
	v_readlane_b32 s1, v232, 3
	v_readlane_b32 s41, v233, 57
	s_cselect_b32 s1, s41, s1
	s_cselect_b32 s0, s40, s0
	v_writelane_b32 v232, s0, 8
	v_mov_b32_e32 v1, v97
	s_waitcnt vmcnt(6)
	s_mov_b32 s66, 0
	v_writelane_b32 v232, s1, 9
	v_readfirstlane_b32 s1, v0
	v_add_u32_e32 v0, v15, v13
	s_sub_i32 s0, 0, s65
	v_add_lshl_u32 v0, v0, v14, 1
	s_mul_i32 s0, s0, s1
	v_lshl_add_u64 v[136:137], s[34:35], 0, v[0:1]
	v_add_u32_e32 v0, v18, v16
	s_mul_hi_u32 s0, s1, s0
	v_add_lshl_u32 v0, v0, v17, 1
	s_mov_b32 s60, s48
	v_lshl_or_b32 v148, s48, 5, v2
	s_add_i32 s68, s1, s0
	v_lshl_add_u64 v[138:139], s[34:35], 0, v[0:1]
	v_add_u32_e32 v149, 0, v4
	s_barrier
	s_waitcnt vmcnt(0)
	s_mov_b32 s51, 0
	v_writelane_b32 v232, s51, 60
	s_branch .LBB0_326

.LBB0_325:
	s_mov_b32 s69, 1
	v_writelane_b32 v232, s69, 60
	s_andn2_b64 vcc, exec, s[40:41]
	s_mov_b32 s69, s67
	s_mov_b32 s46, s70
	s_mov_b64 s[78:79], s[74:75]
	s_mov_b64 s[42:43], s[0:1]
	s_cbranch_vccz .LBB0_398

.LBB0_332:
	s_add_u32 s42, s42, 0x80
	s_addc_u32 s43, s43, 0
	s_add_u32 s48, s78, 0x100
	s_addc_u32 s49, s79, 0
	s_mov_b32 s50, 0
	v_readlane_b32 s51, v232, 60
	s_cmp_eq_u32 s51, 0
	s_cbranch_scc0 .Lk_peel
	v_mov_b32_e32 v0, 0
	v_mov_b32_e32 v1, v0
	v_mov_b32_e32 v2, v0
	v_mov_b32_e32 v3, v0
	v_mov_b32_e32 v4, v0
	v_mov_b32_e32 v5, v0
	v_mov_b32_e32 v6, v0
	v_mov_b32_e32 v7, v0
	v_mov_b32_e32 v16, v0
	v_mov_b32_e32 v17, v0
	v_mov_b32_e32 v18, v0
	v_mov_b32_e32 v19, v0
	v_mov_b32_e32 v20, v0
	v_mov_b32_e32 v21, v0
	v_mov_b32_e32 v22, v0
	v_mov_b32_e32 v23, v0
	v_mov_b32_e32 v32, v0
	v_mov_b32_e32 v33, v0
	v_mov_b32_e32 v34, v0
	v_mov_b32_e32 v35, v0
	v_mov_b32_e32 v36, v0
	v_mov_b32_e32 v37, v0
	v_mov_b32_e32 v38, v0
	v_mov_b32_e32 v39, v0
	v_mov_b32_e32 v48, v0
	v_mov_b32_e32 v49, v0
	v_mov_b32_e32 v50, v0
	v_mov_b32_e32 v51, v0
	v_mov_b32_e32 v52, v0
	v_mov_b32_e32 v53, v0
	v_mov_b32_e32 v54, v0
	v_mov_b32_e32 v55, v0
	v_mov_b32_e32 v8, v0
	v_mov_b32_e32 v9, v0
	v_mov_b32_e32 v10, v0
	v_mov_b32_e32 v11, v0
	v_mov_b32_e32 v12, v0
	v_mov_b32_e32 v13, v0
	v_mov_b32_e32 v14, v0
	v_mov_b32_e32 v15, v0
	v_mov_b32_e32 v24, v0
	v_mov_b32_e32 v25, v0
	v_mov_b32_e32 v26, v0
	v_mov_b32_e32 v27, v0
	v_mov_b32_e32 v28, v0
	v_mov_b32_e32 v29, v0
	v_mov_b32_e32 v30, v0
	v_mov_b32_e32 v31, v0
	v_mov_b32_e32 v40, v0
	v_mov_b32_e32 v41, v0
	v_mov_b32_e32 v42, v0
	v_mov_b32_e32 v43, v0
	v_mov_b32_e32 v44, v0
	v_mov_b32_e32 v45, v0
	v_mov_b32_e32 v46, v0
	v_mov_b32_e32 v47, v0
	v_mov_b32_e32 v56, v0
	v_mov_b32_e32 v57, v0
	v_mov_b32_e32 v58, v0
	v_mov_b32_e32 v59, v0
	v_mov_b32_e32 v60, v0
	v_mov_b32_e32 v61, v0
	v_mov_b32_e32 v62, v0
	v_mov_b32_e32 v63, v0
	v_mov_b32_e32 v64, v0
	v_mov_b32_e32 v65, v0
	v_mov_b32_e32 v66, v0
	v_mov_b32_e32 v67, v0
	v_mov_b32_e32 v68, v0
	v_mov_b32_e32 v69, v0
	v_mov_b32_e32 v70, v0
	v_mov_b32_e32 v71, v0
	v_mov_b32_e32 v80, v0
	v_mov_b32_e32 v81, v0
	v_mov_b32_e32 v82, v0
	v_mov_b32_e32 v83, v0
	v_mov_b32_e32 v84, v0
	v_mov_b32_e32 v85, v0
	v_mov_b32_e32 v86, v0
	v_mov_b32_e32 v87, v0
	v_mov_b32_e32 v98, v0
	v_mov_b32_e32 v99, v0
	v_mov_b32_e32 v100, v0
	v_mov_b32_e32 v101, v0
	v_mov_b32_e32 v102, v0
	v_mov_b32_e32 v103, v0
	v_mov_b32_e32 v104, v0
	v_mov_b32_e32 v105, v0
	v_mov_b32_e32 v114, v0
	v_mov_b32_e32 v115, v0
	v_mov_b32_e32 v116, v0
	v_mov_b32_e32 v117, v0
	v_mov_b32_e32 v118, v0
	v_mov_b32_e32 v119, v0
	v_mov_b32_e32 v120, v0
	v_mov_b32_e32 v121, v0
	v_mov_b32_e32 v72, v0
	v_mov_b32_e32 v73, v0
	v_mov_b32_e32 v74, v0
	v_mov_b32_e32 v75, v0
	v_mov_b32_e32 v76, v0
	v_mov_b32_e32 v77, v0
	v_mov_b32_e32 v78, v0
	v_mov_b32_e32 v79, v0
	v_mov_b32_e32 v88, v0
	v_mov_b32_e32 v89, v0
	v_mov_b32_e32 v90, v0
	v_mov_b32_e32 v91, v0
	v_mov_b32_e32 v92, v0
	v_mov_b32_e32 v93, v0
	v_mov_b32_e32 v94, v0
	v_mov_b32_e32 v95, v0
	v_mov_b32_e32 v106, v0
	v_mov_b32_e32 v107, v0
	v_mov_b32_e32 v108, v0
	v_mov_b32_e32 v109, v0
	v_mov_b32_e32 v110, v0
	v_mov_b32_e32 v111, v0
	v_mov_b32_e32 v112, v0
	v_mov_b32_e32 v113, v0
	v_mov_b32_e32 v122, v0
	v_mov_b32_e32 v123, v0
	v_mov_b32_e32 v124, v0
	v_mov_b32_e32 v125, v0
	v_mov_b32_e32 v126, v0
	v_mov_b32_e32 v127, v0
	v_mov_b32_e32 v128, v0
	v_mov_b32_e32 v129, v0

.Lk_done:
	v_readlane_b32 s42, v233, 50
	v_readlane_b32 s43, v233, 51
	s_and_b64 vcc, exec, s[42:43]
	s_cbranch_vccz .LBB0_336
	s_barrier

.Lk_peel:
	s_add_i32 s51, s50, 2
	s_add_u32 s52, s42, 0x80
	s_addc_u32 s53, s43, 0
	s_add_i32 s54, 0, 0x10000
	s_cmp_eq_u32 s87, s50
	s_cselect_b32 s79, s1, s53
	s_cselect_b32 s78, s0, s52
	v_add_u32_e32 v144, s54, v147
	s_cselect_b32 s53, s75, s49
	s_cselect_b32 s52, s74, s48
	s_add_i32 s50, 0, 0x14000
	s_waitcnt lgkmcnt(0)
	ds_read_b128 v[140:143], v144
	ds_read_b128 v[162:165], v144 offset:1024
	ds_read_b128 v[166:169], v144 offset:2048
	ds_read_b128 v[170:173], v144 offset:3072
	v_add_u32_e32 v144, s50, v147
	ds_read_b128 v[174:177], v144
	ds_read_b128 v[178:181], v144 offset:1024
	ds_read_b128 v[182:185], v144 offset:2048
	ds_read_b128 v[186:189], v144 offset:3072
	v_lshl_add_u64 v[144:145], s[42:43], 0, v[136:137]
	s_add_i32 m0, s9, 0xc000
	ds_read_b128 v[190:193], v149
	ds_read_b128 v[194:197], v149 offset:1024
	ds_read_b128 v[198:201], v149 offset:2048
	ds_read_b128 v[202:205], v149 offset:3072
	ds_read_b128 v[206:209], v149 offset:4096
	ds_read_b128 v[210:213], v149 offset:5120
	ds_read_b128 v[214:217], v149 offset:6144
	ds_read_b128 v[218:221], v149 offset:7168
	global_load_lds_dwordx4 v[144:145], off
	v_lshl_add_u64 v[144:145], s[42:43], 0, v[138:139]
	s_add_i32 m0, s9, 0xe000
	s_nop 0
	global_load_lds_dwordx4 v[144:145], off
	s_waitcnt vmcnt(16)
	s_waitcnt lgkmcnt(0)
	s_barrier
	s_setprio 1
	s_waitcnt lgkmcnt(0)
	v_mfma_f32_16x16x32_bf16 v[126:129], v[140:143], v[190:193], 0
	v_mfma_f32_16x16x32_bf16 v[122:125], v[166:169], v[190:193], 0
	v_mfma_f32_16x16x32_bf16 v[110:113], v[140:143], v[198:201], 0
	v_mfma_f32_16x16x32_bf16 v[106:109], v[166:169], v[198:201], 0
	v_mfma_f32_16x16x32_bf16 v[92:95], v[140:143], v[206:209], 0
	v_mfma_f32_16x16x32_bf16 v[88:91], v[166:169], v[206:209], 0
	v_mfma_f32_16x16x32_bf16 v[76:79], v[140:143], v[214:217], 0
	v_mfma_f32_16x16x32_bf16 v[72:75], v[166:169], v[214:217], 0
	v_mfma_f32_16x16x32_bf16 v[126:129], v[162:165], v[194:197], v[126:129]
	v_mfma_f32_16x16x32_bf16 v[122:125], v[170:173], v[194:197], v[122:125]
	v_mfma_f32_16x16x32_bf16 v[110:113], v[162:165], v[202:205], v[110:113]
	v_mfma_f32_16x16x32_bf16 v[106:109], v[170:173], v[202:205], v[106:109]
	v_mfma_f32_16x16x32_bf16 v[92:95], v[162:165], v[210:213], v[92:95]
	v_mfma_f32_16x16x32_bf16 v[88:91], v[170:173], v[210:213], v[88:91]
	v_mfma_f32_16x16x32_bf16 v[76:79], v[162:165], v[218:221], v[76:79]
	v_mfma_f32_16x16x32_bf16 v[72:75], v[170:173], v[218:221], v[72:75]
	s_setprio 0
	s_setprio 1
	v_mfma_f32_16x16x32_bf16 v[118:121], v[174:177], v[190:193], 0
	v_mfma_f32_16x16x32_bf16 v[114:117], v[182:185], v[190:193], 0
	v_mfma_f32_16x16x32_bf16 v[102:105], v[174:177], v[198:201], 0
	v_mfma_f32_16x16x32_bf16 v[98:101], v[182:185], v[198:201], 0
	v_mfma_f32_16x16x32_bf16 v[84:87], v[174:177], v[206:209], 0
	v_mfma_f32_16x16x32_bf16 v[80:83], v[182:185], v[206:209], 0
	v_mfma_f32_16x16x32_bf16 v[68:71], v[174:177], v[214:217], 0
	v_mfma_f32_16x16x32_bf16 v[64:67], v[182:185], v[214:217], 0
	v_mfma_f32_16x16x32_bf16 v[118:121], v[178:181], v[194:197], v[118:121]
	v_mfma_f32_16x16x32_bf16 v[114:117], v[186:189], v[194:197], v[114:117]
	v_mfma_f32_16x16x32_bf16 v[102:105], v[178:181], v[202:205], v[102:105]
	v_mfma_f32_16x16x32_bf16 v[98:101], v[186:189], v[202:205], v[98:101]
	v_mfma_f32_16x16x32_bf16 v[84:87], v[178:181], v[210:213], v[84:87]
	v_mfma_f32_16x16x32_bf16 v[80:83], v[186:189], v[210:213], v[80:83]
	v_mfma_f32_16x16x32_bf16 v[68:71], v[178:181], v[218:221], v[68:71]
	v_mfma_f32_16x16x32_bf16 v[64:67], v[186:189], v[218:221], v[64:67]
	s_setprio 0
	s_barrier
	s_add_i32 s54, s54, s8
	v_lshl_add_u64 v[144:145], s[52:53], 0, v[96:97]
	s_mov_b32 m0, s54
	ds_read_b128 v[190:193], v149 offset:16384
	ds_read_b128 v[194:197], v149 offset:17408
	ds_read_b128 v[198:201], v149 offset:18432
	ds_read_b128 v[202:205], v149 offset:19456
	ds_read_b128 v[206:209], v149 offset:20480
	ds_read_b128 v[210:213], v149 offset:21504
	ds_read_b128 v[214:217], v149 offset:22528
	ds_read_b128 v[218:221], v149 offset:23552
	global_load_lds_dwordx4 v[144:145], off
	s_add_i32 m0, s54, 0x2000
	v_lshl_add_u64 v[150:151], s[52:53], 0, v[134:135]
	s_add_u32 s52, s52, s34
	s_addc_u32 s53, s53, s35
	s_add_i32 s50, s50, s8
	global_load_lds_dwordx4 v[150:151], off
	v_lshl_add_u64 v[222:223], s[52:53], 0, v[96:97]
	s_mov_b32 m0, s50
	v_lshl_add_u64 v[224:225], s[52:53], 0, v[134:135]
	global_load_lds_dwordx4 v[222:223], off
	s_add_i32 m0, s50, 0x2000
	v_lshl_add_u64 v[226:227], s[78:79], 0, v[130:131]
	global_load_lds_dwordx4 v[224:225], off
	s_mov_b32 m0, s9
	v_lshl_add_u64 v[228:229], s[78:79], 0, v[132:133]
	global_load_lds_dwordx4 v[226:227], off
	s_mov_b32 m0, s98
	s_nop 0
	global_load_lds_dwordx4 v[228:229], off
	s_waitcnt vmcnt(16)
	s_waitcnt lgkmcnt(0)
	s_barrier
	s_setprio 1
	s_waitcnt lgkmcnt(0)
	v_mfma_f32_16x16x32_bf16 v[60:63], v[140:143], v[190:193], 0
	v_mfma_f32_16x16x32_bf16 v[56:59], v[166:169], v[190:193], 0
	v_mfma_f32_16x16x32_bf16 v[44:47], v[140:143], v[198:201], 0
	v_mfma_f32_16x16x32_bf16 v[40:43], v[166:169], v[198:201], 0
	v_mfma_f32_16x16x32_bf16 v[28:31], v[140:143], v[206:209], 0
	v_mfma_f32_16x16x32_bf16 v[24:27], v[166:169], v[206:209], 0
	v_mfma_f32_16x16x32_bf16 v[12:15], v[140:143], v[214:217], 0
	v_mfma_f32_16x16x32_bf16 v[8:11], v[166:169], v[214:217], 0
	v_mfma_f32_16x16x32_bf16 v[60:63], v[162:165], v[194:197], v[60:63]
	v_mfma_f32_16x16x32_bf16 v[56:59], v[170:173], v[194:197], v[56:59]
	v_mfma_f32_16x16x32_bf16 v[44:47], v[162:165], v[202:205], v[44:47]
	v_mfma_f32_16x16x32_bf16 v[40:43], v[170:173], v[202:205], v[40:43]
	v_mfma_f32_16x16x32_bf16 v[28:31], v[162:165], v[210:213], v[28:31]
	v_mfma_f32_16x16x32_bf16 v[24:27], v[170:173], v[210:213], v[24:27]
	v_mfma_f32_16x16x32_bf16 v[12:15], v[162:165], v[218:221], v[12:15]
	v_mfma_f32_16x16x32_bf16 v[8:11], v[170:173], v[218:221], v[8:11]
	s_setprio 0
	s_setprio 1
	v_mfma_f32_16x16x32_bf16 v[52:55], v[174:177], v[190:193], 0
	v_mfma_f32_16x16x32_bf16 v[48:51], v[182:185], v[190:193], 0
	v_mfma_f32_16x16x32_bf16 v[36:39], v[174:177], v[198:201], 0
	v_mfma_f32_16x16x32_bf16 v[32:35], v[182:185], v[198:201], 0
	v_mfma_f32_16x16x32_bf16 v[20:23], v[174:177], v[206:209], 0
	v_mfma_f32_16x16x32_bf16 v[16:19], v[182:185], v[206:209], 0
	v_mfma_f32_16x16x32_bf16 v[4:7], v[174:177], v[214:217], 0
	v_mfma_f32_16x16x32_bf16 v[0:3], v[182:185], v[214:217], 0
	v_mfma_f32_16x16x32_bf16 v[52:55], v[178:181], v[194:197], v[52:55]
	v_mfma_f32_16x16x32_bf16 v[48:51], v[186:189], v[194:197], v[48:51]
	v_mfma_f32_16x16x32_bf16 v[36:39], v[178:181], v[202:205], v[36:39]
	v_mfma_f32_16x16x32_bf16 v[32:35], v[186:189], v[202:205], v[32:35]
	v_mfma_f32_16x16x32_bf16 v[20:23], v[178:181], v[210:213], v[20:23]
	v_mfma_f32_16x16x32_bf16 v[16:19], v[186:189], v[210:213], v[16:19]
	v_mfma_f32_16x16x32_bf16 v[4:7], v[178:181], v[218:221], v[4:7]
	v_mfma_f32_16x16x32_bf16 v[0:3], v[186:189], v[218:221], v[0:3]
	s_setprio 0
	s_barrier
	s_add_i32 s50, 0, 0x18000
	v_add_u32_e32 v161, s50, v147
	s_add_i32 s54, 0, 0x1c000
	ds_read_b128 v[140:143], v161
	ds_read_b128 v[162:165], v161 offset:1024
	ds_read_b128 v[166:169], v161 offset:2048
	ds_read_b128 v[170:173], v161 offset:3072
	v_add_u32_e32 v161, s54, v147
	ds_read_b128 v[174:177], v161
	ds_read_b128 v[178:181], v161 offset:1024
	ds_read_b128 v[182:185], v161 offset:2048
	ds_read_b128 v[186:189], v161 offset:3072
	s_add_u32 s52, s78, s34
	s_addc_u32 s53, s79, s35
	s_mov_b32 m0, s99
	v_lshl_add_u64 v[230:231], s[52:53], 0, v[130:131]
	ds_read_b128 v[190:193], v149 offset:32768
	ds_read_b128 v[194:197], v149 offset:33792
	ds_read_b128 v[198:201], v149 offset:34816
	ds_read_b128 v[202:205], v149 offset:35840
	ds_read_b128 v[206:209], v149 offset:36864
	ds_read_b128 v[210:213], v149 offset:37888
	ds_read_b128 v[214:217], v149 offset:38912
	ds_read_b128 v[218:221], v149 offset:39936
	global_load_lds_dwordx4 v[230:231], off
	v_lshl_add_u64 v[230:231], s[52:53], 0, v[132:133]
	s_mov_b32 m0, s76
	s_nop 0
	global_load_lds_dwordx4 v[230:231], off
	s_waitcnt vmcnt(8)
	s_waitcnt lgkmcnt(0)
	s_barrier
	s_setprio 1
	s_waitcnt lgkmcnt(0)
	v_mfma_f32_16x16x32_bf16 v[126:129], v[140:143], v[190:193], v[126:129]
	v_mfma_f32_16x16x32_bf16 v[122:125], v[166:169], v[190:193], v[122:125]
	v_mfma_f32_16x16x32_bf16 v[110:113], v[140:143], v[198:201], v[110:113]
	v_mfma_f32_16x16x32_bf16 v[106:109], v[166:169], v[198:201], v[106:109]
	v_mfma_f32_16x16x32_bf16 v[92:95], v[140:143], v[206:209], v[92:95]
	v_mfma_f32_16x16x32_bf16 v[88:91], v[166:169], v[206:209], v[88:91]
	v_mfma_f32_16x16x32_bf16 v[76:79], v[140:143], v[214:217], v[76:79]
	v_mfma_f32_16x16x32_bf16 v[72:75], v[166:169], v[214:217], v[72:75]
	v_mfma_f32_16x16x32_bf16 v[126:129], v[162:165], v[194:197], v[126:129]
	v_mfma_f32_16x16x32_bf16 v[122:125], v[170:173], v[194:197], v[122:125]
	v_mfma_f32_16x16x32_bf16 v[110:113], v[162:165], v[202:205], v[110:113]
	v_mfma_f32_16x16x32_bf16 v[106:109], v[170:173], v[202:205], v[106:109]
	v_mfma_f32_16x16x32_bf16 v[92:95], v[162:165], v[210:213], v[92:95]
	v_mfma_f32_16x16x32_bf16 v[88:91], v[170:173], v[210:213], v[88:91]
	v_mfma_f32_16x16x32_bf16 v[76:79], v[162:165], v[218:221], v[76:79]
	v_mfma_f32_16x16x32_bf16 v[72:75], v[170:173], v[218:221], v[72:75]
	s_setprio 0
	s_setprio 1
	v_mfma_f32_16x16x32_bf16 v[118:121], v[174:177], v[190:193], v[118:121]
	v_mfma_f32_16x16x32_bf16 v[114:117], v[182:185], v[190:193], v[114:117]
	v_mfma_f32_16x16x32_bf16 v[102:105], v[174:177], v[198:201], v[102:105]
	v_mfma_f32_16x16x32_bf16 v[98:101], v[182:185], v[198:201], v[98:101]
	v_mfma_f32_16x16x32_bf16 v[84:87], v[174:177], v[206:209], v[84:87]
	v_mfma_f32_16x16x32_bf16 v[80:83], v[182:185], v[206:209], v[80:83]
	v_mfma_f32_16x16x32_bf16 v[68:71], v[174:177], v[214:217], v[68:71]
	v_mfma_f32_16x16x32_bf16 v[64:67], v[182:185], v[214:217], v[64:67]
	v_mfma_f32_16x16x32_bf16 v[118:121], v[178:181], v[194:197], v[118:121]
	v_mfma_f32_16x16x32_bf16 v[114:117], v[186:189], v[194:197], v[114:117]
	v_mfma_f32_16x16x32_bf16 v[102:105], v[178:181], v[202:205], v[102:105]
	v_mfma_f32_16x16x32_bf16 v[98:101], v[186:189], v[202:205], v[98:101]
	v_mfma_f32_16x16x32_bf16 v[84:87], v[178:181], v[210:213], v[84:87]
	v_mfma_f32_16x16x32_bf16 v[80:83], v[186:189], v[210:213], v[80:83]
	v_mfma_f32_16x16x32_bf16 v[68:71], v[178:181], v[218:221], v[68:71]
	v_mfma_f32_16x16x32_bf16 v[64:67], v[186:189], v[218:221], v[64:67]
	s_setprio 0
	s_barrier
	s_add_i32 s50, s50, s8
	v_lshl_add_u64 v[144:145], v[144:145], 0, s[12:13]
	s_mov_b32 m0, s50
	ds_read_b128 v[190:193], v149 offset:49152
	ds_read_b128 v[194:197], v149 offset:50176
	ds_read_b128 v[198:201], v149 offset:51200
	ds_read_b128 v[202:205], v149 offset:52224
	ds_read_b128 v[206:209], v149 offset:53248
	ds_read_b128 v[210:213], v149 offset:54272
	ds_read_b128 v[214:217], v149 offset:55296
	ds_read_b128 v[218:221], v149 offset:56320
	global_load_lds_dwordx4 v[144:145], off
	v_lshl_add_u64 v[144:145], v[150:151], 0, s[12:13]
	s_add_i32 m0, s50, 0x2000
	s_add_i32 s50, s54, s8
	global_load_lds_dwordx4 v[144:145], off
	v_lshl_add_u64 v[144:145], v[222:223], 0, s[12:13]
	s_mov_b32 m0, s50
	s_nop 0
	global_load_lds_dwordx4 v[144:145], off
	v_lshl_add_u64 v[144:145], v[224:225], 0, s[12:13]
	s_add_i32 m0, s50, 0x2000
	s_nop 0
	global_load_lds_dwordx4 v[144:145], off
	v_lshl_add_u64 v[144:145], v[226:227], 0, s[12:13]
	s_mov_b32 m0, s77
	s_nop 0
	global_load_lds_dwordx4 v[144:145], off
	v_lshl_add_u64 v[144:145], v[228:229], 0, s[12:13]
	s_mov_b32 m0, s86
	s_nop 0
	global_load_lds_dwordx4 v[144:145], off
	s_waitcnt vmcnt(8)
	s_waitcnt lgkmcnt(0)
	s_barrier
	s_setprio 1
	s_waitcnt lgkmcnt(0)
	v_mfma_f32_16x16x32_bf16 v[60:63], v[140:143], v[190:193], v[60:63]
	v_mfma_f32_16x16x32_bf16 v[56:59], v[166:169], v[190:193], v[56:59]
	v_mfma_f32_16x16x32_bf16 v[44:47], v[140:143], v[198:201], v[44:47]
	v_mfma_f32_16x16x32_bf16 v[40:43], v[166:169], v[198:201], v[40:43]
	v_mfma_f32_16x16x32_bf16 v[28:31], v[140:143], v[206:209], v[28:31]
	v_mfma_f32_16x16x32_bf16 v[24:27], v[166:169], v[206:209], v[24:27]
	v_mfma_f32_16x16x32_bf16 v[12:15], v[140:143], v[214:217], v[12:15]
	v_mfma_f32_16x16x32_bf16 v[8:11], v[166:169], v[214:217], v[8:11]
	v_mfma_f32_16x16x32_bf16 v[60:63], v[162:165], v[194:197], v[60:63]
	v_mfma_f32_16x16x32_bf16 v[56:59], v[170:173], v[194:197], v[56:59]
	v_mfma_f32_16x16x32_bf16 v[44:47], v[162:165], v[202:205], v[44:47]
	v_mfma_f32_16x16x32_bf16 v[40:43], v[170:173], v[202:205], v[40:43]
	v_mfma_f32_16x16x32_bf16 v[28:31], v[162:165], v[210:213], v[28:31]
	v_mfma_f32_16x16x32_bf16 v[24:27], v[170:173], v[210:213], v[24:27]
	v_mfma_f32_16x16x32_bf16 v[12:15], v[162:165], v[218:221], v[12:15]
	v_mfma_f32_16x16x32_bf16 v[8:11], v[170:173], v[218:221], v[8:11]
	s_setprio 0
	s_setprio 1
	v_mfma_f32_16x16x32_bf16 v[52:55], v[174:177], v[190:193], v[52:55]
	v_mfma_f32_16x16x32_bf16 v[48:51], v[182:185], v[190:193], v[48:51]
	v_mfma_f32_16x16x32_bf16 v[36:39], v[174:177], v[198:201], v[36:39]
	v_mfma_f32_16x16x32_bf16 v[32:35], v[182:185], v[198:201], v[32:35]
	v_mfma_f32_16x16x32_bf16 v[20:23], v[174:177], v[206:209], v[20:23]
	v_mfma_f32_16x16x32_bf16 v[16:19], v[182:185], v[206:209], v[16:19]
	v_mfma_f32_16x16x32_bf16 v[4:7], v[174:177], v[214:217], v[4:7]
	v_mfma_f32_16x16x32_bf16 v[0:3], v[182:185], v[214:217], v[0:3]
	v_mfma_f32_16x16x32_bf16 v[52:55], v[178:181], v[194:197], v[52:55]
	v_mfma_f32_16x16x32_bf16 v[48:51], v[186:189], v[194:197], v[48:51]
	v_mfma_f32_16x16x32_bf16 v[36:39], v[178:181], v[202:205], v[36:39]
	v_mfma_f32_16x16x32_bf16 v[32:35], v[186:189], v[202:205], v[32:35]
	v_mfma_f32_16x16x32_bf16 v[20:23], v[178:181], v[210:213], v[20:23]
	v_mfma_f32_16x16x32_bf16 v[16:19], v[186:189], v[210:213], v[16:19]
	v_mfma_f32_16x16x32_bf16 v[4:7], v[178:181], v[218:221], v[4:7]
	v_mfma_f32_16x16x32_bf16 v[0:3], v[186:189], v[218:221], v[0:3]
	s_setprio 0
	s_barrier
	s_add_u32 s42, s42, 0x100
	s_addc_u32 s43, s43, 0
	s_add_u32 s48, s48, 0x100
	s_addc_u32 s49, s49, 0
	s_cmp_ge_u32 s51, s64
	s_mov_b32 s50, s51
	s_cbranch_scc0 .LBB0_333
	s_branch .Lk_done
